# sharded/seeded queues with the per-shard offset computed from the actual grid size (correct for any grid)
# speedup vs baseline: 1.0021x; 1.0021x over previous
.LBB0_24:
	s_or_b64 exec, exec, s[0:1]
	s_waitcnt lgkmcnt(0)
	s_barrier
	ds_read_b32 v1, v161
	s_waitcnt lgkmcnt(0)
	v_readfirstlane_b32 s10, v1
	v_readlane_b32 s98, v255, 14
	s_cmp_eq_u32 s98, 0
	s_cbranch_scc0 .Lsdp1_first
	v_readlane_b32 s98, v254, 20
	s_and_b32 s98, s98, 7
	s_lshl_b32 s10, s10, 3
	s_add_i32 s10, s10, s98
	v_readlane_b32 s99, v255, 13
	s_sub_i32 s99, s99, s98
	s_add_i32 s99, s99, 7
	s_and_b32 s99, s99, -8
	s_add_i32 s10, s10, s99

.LBB0_72:
	s_or_b64 exec, exec, s[0:1]
	s_waitcnt lgkmcnt(0)
	s_barrier
	ds_read_b32 v1, v161
	s_waitcnt lgkmcnt(0)
	v_readfirstlane_b32 s0, v1
	v_readlane_b32 s98, v254, 20
	s_and_b32 s98, s98, 7
	s_lshl_b32 s0, s0, 3
	s_add_i32 s0, s0, s98
	v_readlane_b32 s99, v255, 13
	s_sub_i32 s99, s99, s98
	s_add_i32 s99, s99, 7
	s_and_b32 s99, s99, -8
	s_add_i32 s0, s0, s99
	s_cmp_ge_i32 s0, s14
	s_cbranch_scc1 .LBB0_117

.LBB0_173:
	s_or_b64 exec, exec, s[0:1]
	s_waitcnt lgkmcnt(0)
	s_barrier
	ds_read_b32 v1, v161
	s_waitcnt lgkmcnt(0)
	v_readfirstlane_b32 s20, v1
	v_readlane_b32 s98, v254, 20
	s_and_b32 s98, s98, 7
	s_lshl_b32 s20, s20, 3
	s_add_i32 s20, s20, s98
	v_readlane_b32 s99, v255, 13
	s_sub_i32 s99, s99, s98
	s_add_i32 s99, s99, 7
	s_and_b32 s99, s99, -8
	s_add_i32 s20, s20, s99
	s_cmp_ge_i32 s20, s18
	s_cbranch_scc1 .LBB0_287

.LBB0_295:
	s_or_b64 exec, exec, s[2:3]
	s_waitcnt lgkmcnt(0)
	s_barrier
	ds_read_b32 v1, v161
	s_waitcnt lgkmcnt(0)
	v_readfirstlane_b32 s14, v1
	v_readlane_b32 s98, v254, 20
	s_and_b32 s98, s98, 7
	s_lshl_b32 s14, s14, 3
	s_add_i32 s14, s14, s98
	v_readlane_b32 s99, v255, 13
	s_sub_i32 s99, s99, s98
	s_add_i32 s99, s99, 7
	s_and_b32 s99, s99, -8
	s_add_i32 s14, s14, s99
	s_cmpk_gt_i32 s14, 0x83f
	s_cbranch_scc1 .LBB0_398

.LBB0_409:
	s_or_b64 exec, exec, s[0:1]
	s_waitcnt lgkmcnt(0)
	s_barrier
	ds_read_b32 v1, v161
	s_waitcnt lgkmcnt(0)
	v_readfirstlane_b32 s2, v1
	v_readlane_b32 s98, v254, 20
	s_and_b32 s98, s98, 7
	s_lshl_b32 s2, s2, 3
	s_add_i32 s2, s2, s98
	v_readlane_b32 s99, v255, 13
	s_sub_i32 s99, s99, s98
	s_add_i32 s99, s99, 7
	s_and_b32 s99, s99, -8
	s_add_i32 s2, s2, s99
	s_cmpk_gt_i32 s2, 0x113f
	s_cbranch_scc1 .LBB0_447

.LBB0_456:
	s_or_b64 exec, exec, s[0:1]
	s_waitcnt lgkmcnt(0)
	s_barrier
	ds_read_b32 v1, v161
	s_waitcnt lgkmcnt(0)
	v_readfirstlane_b32 s21, v1
	v_readlane_b32 s98, v254, 20
	s_and_b32 s98, s98, 7
	s_lshl_b32 s21, s21, 3
	s_add_i32 s21, s21, s98
	v_readlane_b32 s99, v255, 13
	s_sub_i32 s99, s99, s98
	s_add_i32 s99, s99, 7
	s_and_b32 s99, s99, -8
	s_add_i32 s21, s21, s99
	s_cmp_ge_i32 s21, s17
	s_cbranch_scc1 .LBB0_559

.LBB0_570:
	s_or_b64 exec, exec, s[4:5]
	s_waitcnt lgkmcnt(0)
	s_barrier
	ds_read_b32 v1, v161
	v_readlane_b32 s0, v254, 49
	s_waitcnt lgkmcnt(0)
	v_readfirstlane_b32 s18, v1
	v_readlane_b32 s98, v254, 20
	s_and_b32 s98, s98, 7
	s_lshl_b32 s18, s18, 3
	s_add_i32 s18, s18, s98
	v_readlane_b32 s99, v255, 13
	s_sub_i32 s99, s99, s98
	s_add_i32 s99, s99, 7
	s_and_b32 s99, s99, -8
	s_add_i32 s18, s18, s99
	s_cmp_ge_i32 s18, s0
	s_cbranch_scc1 .LBB0_740

.LBB0_876:
	s_or_b64 exec, exec, s[0:1]
	s_waitcnt lgkmcnt(0)
	s_barrier
	ds_read_b32 v1, v161
	s_waitcnt lgkmcnt(0)
	v_readfirstlane_b32 s18, v1
	v_readlane_b32 s98, v255, 14
	s_cmp_eq_u32 s98, 0
	s_cbranch_scc0 .Lsdp0_first
	v_readlane_b32 s98, v254, 20
	s_and_b32 s98, s98, 7
	s_lshl_b32 s18, s18, 3
	s_add_i32 s18, s18, s98
	v_readlane_b32 s99, v255, 13
	s_sub_i32 s99, s99, s98
	s_add_i32 s99, s99, 7
	s_and_b32 s99, s99, -8
	s_add_i32 s18, s18, s99
